# also nt: the full-line conv output stores
# speedup vs baseline: 1.0014x; 1.0014x over previous
.LBB0_411:
	v_max_i32_e32 v2, 2, v80
	v_add_u32_e32 v0, -2, v2
	v_mov_b32_e32 v1, v195
	v_lshlrev_b64 v[0:1], 11, v[0:1]
	v_lshl_add_u64 v[0:1], v[128:129], 0, v[0:1]
	global_load_dwordx4 v[24:27], v[0:1], off
	v_mov_b32_e32 v1, v195
	v_add_u32_e32 v0, -1, v2
	v_lshlrev_b64 v[0:1], 11, v[0:1]
	v_lshl_add_u64 v[0:1], v[128:129], 0, v[0:1]
	global_load_dwordx4 v[28:31], v[0:1], off
	v_add_u32_e32 v0, 0xffffc000, v80
	s_movk_i32 s0, 0x4000
	v_lshrrev_b32_e32 v194, 5, v0
	v_cmp_gt_i32_e32 vcc, s0, v80
	v_lshlrev_b64 v[0:1], 11, v[194:195]
	v_and_b32_e32 v3, 0x7f0, v80
	v_cndmask_b32_e64 v1, v1, 0, vcc
	v_cndmask_b32_e64 v0, v0, 0, vcc
	v_lshl_add_u64 v[0:1], v[0:1], 2, v[130:131]
	global_load_dwordx4 v[32:35], v[0:1], off
	global_load_dwordx4 v[36:39], v[0:1], off offset:16
	s_movk_i32 s0, 0x1000
	v_cndmask_b32_e32 v104, v158, v3, vcc
	v_lshl_add_u64 v[2:3], v[0:1], 0, s[24:25]
	v_add_co_u32_e64 v0, s[0:1], s0, v0
	v_ashrrev_i32_e32 v81, 31, v80
	s_nop 0
	v_addc_co_u32_e64 v1, s[0:1], 0, v1, s[0:1]
	global_load_dwordx4 v[40:43], v[0:1], off
	global_load_dwordx4 v[44:47], v[2:3], off offset:16
	s_nop 0
	global_load_dwordx4 v[0:3], v[122:123], off offset:16
	global_load_dwordx4 v[12:15], v[122:123], off
	global_load_dwordx4 v[4:7], v[124:125], off offset:16
	global_load_dwordx4 v[16:19], v[124:125], off
	global_load_dwordx4 v[8:11], v[126:127], off offset:16
	global_load_dwordx4 v[20:23], v[126:127], off
	v_lshlrev_b32_e32 v105, 1, v120
	s_waitcnt vmcnt(12)
	v_lshlrev_b64 v[100:101], 11, v[80:81]
	v_or_b32_e32 v48, v100, v105
	v_mov_b32_e32 v49, v101
	v_lshl_add_u64 v[50:51], s[74:75], 0, v[48:49]
	v_lshl_add_u64 v[48:49], s[76:77], 0, v[48:49]
	global_load_dwordx4 v[56:59], v[50:51], off
	global_load_dwordx4 v[106:109], v[48:49], off
	v_cmp_eq_u32_e64 s[0:1], 0, v104
	v_lshl_add_u64 v[100:101], v[132:133], 0, v[100:101]
	s_waitcnt vmcnt(13)
	v_and_b32_e32 v48, 0xffff0000, v24
	v_lshlrev_b32_e32 v24, 16, v24
	v_lshlrev_b32_e32 v49, 16, v25
	v_and_b32_e32 v25, 0xffff0000, v25
	v_lshlrev_b32_e32 v50, 16, v26
	s_waitcnt vmcnt(12)
	v_lshlrev_b32_e32 v52, 16, v28
	v_lshlrev_b32_e32 v53, 16, v29
	v_and_b32_e32 v29, 0xffff0000, v29
	v_lshlrev_b32_e32 v55, 16, v31
	v_and_b32_e32 v31, 0xffff0000, v31
	v_and_b32_e32 v26, 0xffff0000, v26
	v_lshlrev_b32_e32 v51, 16, v27
	v_and_b32_e32 v27, 0xffff0000, v27
	v_and_b32_e32 v28, 0xffff0000, v28
	s_waitcnt vmcnt(11)
	v_cndmask_b32_e64 v32, v32, 0, vcc
	v_cndmask_b32_e64 v114, v24, v32, s[0:1]
	v_cndmask_b32_e64 v35, v35, 0, vcc
	s_waitcnt vmcnt(9)
	v_cndmask_b32_e64 v24, v40, 0, vcc
	v_cndmask_b32_e64 v81, v52, v24, s[0:1]
	v_cndmask_b32_e64 v24, v43, 0, vcc
	v_cndmask_b32_e64 v174, v29, v24, s[0:1]
	s_waitcnt vmcnt(8)
	v_cndmask_b32_e64 v24, v47, 0, vcc
	v_cndmask_b32_e64 v175, v31, v24, s[0:1]
	v_add_u32_e32 v24, 1, v80
	v_cndmask_b32_e64 v98, v25, v35, s[0:1]
	v_ashrrev_i32_e32 v25, 31, v24
	v_cndmask_b32_e64 v37, v37, 0, vcc
	v_lshlrev_b64 v[94:95], 11, v[24:25]
	v_cndmask_b32_e64 v39, v39, 0, vcc
	v_cndmask_b32_e64 v154, v26, v37, s[0:1]
	v_cndmask_b32_e64 v26, v41, 0, vcc
	v_or_b32_e32 v24, v94, v105
	v_mov_b32_e32 v25, v95
	v_cndmask_b32_e64 v99, v28, v26, s[0:1]
	v_cndmask_b32_e64 v96, v27, v39, s[0:1]
	v_lshl_add_u64 v[26:27], s[74:75], 0, v[24:25]
	v_lshl_add_u64 v[24:25], s[76:77], 0, v[24:25]
	global_load_dwordx4 v[76:79], v[26:27], off nt
	global_load_dwordx4 v[110:113], v[24:25], off
	v_add_u32_e32 v24, 2, v80
	v_ashrrev_i32_e32 v25, 31, v24
	v_lshlrev_b64 v[92:93], 11, v[24:25]
	v_or_b32_e32 v24, v92, v105
	v_mov_b32_e32 v25, v93
	v_lshl_add_u64 v[26:27], s[74:75], 0, v[24:25]
	v_lshl_add_u64 v[24:25], s[76:77], 0, v[24:25]
	global_load_dwordx4 v[72:75], v[26:27], off nt
	global_load_dwordx4 v[68:71], v[24:25], off
	v_add_u32_e32 v24, 3, v80
	v_ashrrev_i32_e32 v25, 31, v24
	v_lshlrev_b64 v[90:91], 11, v[24:25]
	v_or_b32_e32 v24, v90, v105
	v_mov_b32_e32 v25, v91
	v_lshl_add_u64 v[26:27], s[74:75], 0, v[24:25]
	v_lshl_add_u64 v[24:25], s[76:77], 0, v[24:25]
	global_load_dwordx4 v[64:67], v[26:27], off nt
	global_load_dwordx4 v[60:63], v[24:25], off
	s_waitcnt vmcnt(6)
	v_lshlrev_b32_e32 v117, 16, v106
	v_and_b32_e32 v155, 0xffff0000, v106
	v_lshlrev_b32_e32 v176, 16, v107
	v_and_b32_e32 v177, 0xffff0000, v107
	v_mov_b32_e32 v106, v12
	v_mov_b32_e32 v107, v20
	v_add_u32_e32 v24, 4, v80
	v_ashrrev_i32_e32 v25, 31, v24
	v_cndmask_b32_e64 v36, v36, 0, vcc
	v_lshlrev_b64 v[88:89], 11, v[24:25]
	v_lshlrev_b32_e32 v54, 16, v30
	v_cndmask_b32_e64 v34, v34, 0, vcc
	v_cndmask_b32_e64 v116, v50, v36, s[0:1]
	v_cndmask_b32_e64 v32, v44, 0, vcc
	v_or_b32_e32 v24, v88, v105
	v_mov_b32_e32 v25, v89
	v_lshlrev_b32_e32 v119, 16, v108
	v_and_b32_e32 v157, 0xffff0000, v108
	v_lshlrev_b32_e32 v178, 16, v109
	v_and_b32_e32 v179, 0xffff0000, v109
	v_mov_b32_e32 v108, v0
	v_mov_b32_e32 v109, v8
	v_cndmask_b32_e64 v33, v33, 0, vcc
	v_cndmask_b32_e64 v38, v38, 0, vcc
	v_cndmask_b32_e64 v156, v49, v34, s[0:1]
	v_cndmask_b32_e64 v34, v42, 0, vcc
	v_cndmask_b32_e64 v36, v46, 0, vcc
	v_cndmask_b32_e64 v97, v54, v32, s[0:1]
	v_lshl_add_u64 v[26:27], s[74:75], 0, v[24:25]
	v_cndmask_b32_e64 v118, v48, v33, s[0:1]
	v_cndmask_b32_e64 v102, v51, v38, s[0:1]
	v_cndmask_b32_e64 v172, v53, v34, s[0:1]
	v_cndmask_b32_e64 v173, v55, v36, s[0:1]
	v_lshl_add_u64 v[24:25], s[76:77], 0, v[24:25]
	global_load_dwordx4 v[52:55], v[26:27], off nt
	global_load_dwordx4 v[48:51], v[24:25], off
	v_mov_b32_e32 v160, v13
	v_mov_b32_e32 v161, v21
	v_add_u32_e32 v24, 5, v80
	v_ashrrev_i32_e32 v25, 31, v24
	v_lshlrev_b64 v[86:87], 11, v[24:25]
	v_and_b32_e32 v30, 0xffff0000, v30
	v_cndmask_b32_e64 v33, v45, 0, vcc
	v_or_b32_e32 v24, v86, v105
	v_mov_b32_e32 v25, v87
	v_mov_b32_e32 v162, v1
	v_mov_b32_e32 v163, v9
	v_cndmask_b32_e64 v103, v30, v33, s[0:1]
	v_lshl_add_u64 v[26:27], s[74:75], 0, v[24:25]
	v_lshl_add_u64 v[24:25], s[76:77], 0, v[24:25]
	global_load_dwordx4 v[44:47], v[26:27], off nt
	global_load_dwordx4 v[40:43], v[24:25], off
	v_mov_b32_e32 v164, v14
	v_mov_b32_e32 v165, v22
	v_add_u32_e32 v24, 6, v80
	v_ashrrev_i32_e32 v25, 31, v24
	v_lshlrev_b64 v[84:85], 11, v[24:25]
	v_or_b32_e32 v24, v84, v105
	v_mov_b32_e32 v25, v85
	v_mov_b32_e32 v166, v2
	v_mov_b32_e32 v167, v10
	v_lshl_add_u64 v[26:27], s[74:75], 0, v[24:25]
	v_lshl_add_u64 v[24:25], s[76:77], 0, v[24:25]
	global_load_dwordx4 v[36:39], v[26:27], off nt
	global_load_dwordx4 v[32:35], v[24:25], off
	v_add_u32_e32 v24, 7, v80
	s_waitcnt vmcnt(10)
	v_lshlrev_b32_e32 v180, 16, v110
	v_and_b32_e32 v181, 0xffff0000, v110
	v_lshlrev_b32_e32 v110, 16, v56
	v_mov_b32_e32 v115, v110
	v_pk_mul_f32 v[106:107], v[106:107], v[114:115]
	v_lshlrev_b32_e32 v182, 16, v111
	v_fma_f32 v106, v16, v81, v106
	v_add_f32_e32 v106, v106, v107
	v_and_b32_e32 v183, 0xffff0000, v111
	v_lshlrev_b32_e32 v111, 16, v76
	v_mul_f32_e32 v114, v106, v117
	v_mov_b32_e32 v106, v16
	v_mov_b32_e32 v107, v20
	v_pk_mul_f32 v[106:107], v[106:107], v[110:111]
	v_lshlrev_b32_e32 v184, 16, v112
	v_fma_f32 v81, v12, v81, v106
	v_lshlrev_b32_e32 v106, 16, v58
	v_mov_b32_e32 v117, v106
	v_pk_mul_f32 v[108:109], v[108:109], v[116:117]
	v_add_f32_e32 v81, v81, v107
	v_fma_f32 v108, v4, v97, v108
	v_add_f32_e32 v108, v108, v109
	v_lshlrev_b32_e32 v107, 16, v78
	v_mul_f32_e32 v116, v108, v119
	v_mov_b32_e32 v108, v4
	v_mov_b32_e32 v109, v8
	v_pk_mul_f32 v[108:109], v[108:109], v[106:107]
	v_and_b32_e32 v185, 0xffff0000, v112
	v_fma_f32 v97, v0, v97, v108
	v_and_b32_e32 v108, 0xffff0000, v56
	v_mov_b32_e32 v119, v108
	v_lshlrev_b32_e32 v186, 16, v113
	v_and_b32_e32 v187, 0xffff0000, v113
	v_pk_mul_f32 v[112:113], v[160:161], v[118:119]
	v_add_f32_e32 v97, v97, v109
	v_fma_f32 v56, v17, v99, v112
	v_and_b32_e32 v109, 0xffff0000, v76
	v_add_f32_e32 v56, v56, v113
	v_mov_b32_e32 v112, v17
	v_mov_b32_e32 v113, v21
	v_pk_mul_f32 v[112:113], v[112:113], v[108:109]
	v_mul_f32_e32 v56, v56, v155
	v_fma_f32 v76, v13, v99, v112
	v_and_b32_e32 v112, 0xffff0000, v58
	v_mov_b32_e32 v155, v112
	v_cvt_pk_bf16_f32 v56, v114, v56
	v_pk_mul_f32 v[114:115], v[162:163], v[154:155]
	v_add_f32_e32 v76, v76, v113
	v_fma_f32 v58, v5, v103, v114
	v_and_b32_e32 v113, 0xffff0000, v78
	v_add_f32_e32 v58, v58, v115
	v_mov_b32_e32 v114, v5
	v_mov_b32_e32 v115, v9
	v_pk_mul_f32 v[114:115], v[114:115], v[112:113]
	v_mul_f32_e32 v118, v76, v181
	v_fma_f32 v76, v1, v103, v114
	v_lshlrev_b32_e32 v114, 16, v57
	v_mul_f32_e32 v58, v58, v157
	v_mov_b32_e32 v157, v114
	v_cvt_pk_bf16_f32 v58, v116, v58
	v_add_f32_e32 v76, v76, v115
	v_pk_mul_f32 v[116:117], v[164:165], v[156:157]
	v_mul_f32_e32 v119, v76, v185
	v_fma_f32 v76, v18, v172, v116
	v_lshlrev_b32_e32 v115, 16, v77
	v_add_f32_e32 v76, v76, v117
	v_mov_b32_e32 v116, v18
	v_mov_b32_e32 v117, v22
	v_pk_mul_f32 v[116:117], v[116:117], v[114:115]
	v_mul_f32_e32 v78, v76, v176
	v_fma_f32 v76, v14, v172, v116
	v_lshlrev_b32_e32 v116, 16, v59
	v_mov_b32_e32 v103, v116
	v_add_f32_e32 v76, v76, v117
	v_pk_mul_f32 v[102:103], v[166:167], v[102:103]
	v_mul_f32_e32 v154, v76, v182
	v_fma_f32 v76, v6, v173, v102
	v_lshlrev_b32_e32 v117, 16, v79
	v_add_f32_e32 v76, v76, v103
	v_mov_b32_e32 v102, v6
	v_mov_b32_e32 v103, v10
	v_pk_mul_f32 v[102:103], v[102:103], v[116:117]
	v_mul_f32_e32 v155, v76, v178
	v_fma_f32 v76, v2, v173, v102
	v_ashrrev_i32_e32 v25, 31, v24
	v_add_f32_e32 v76, v76, v103
	v_lshlrev_b64 v[82:83], 11, v[24:25]
	v_mul_f32_e32 v102, v76, v186
	v_and_b32_e32 v76, 0xffff0000, v57
	v_or_b32_e32 v24, v82, v105
	v_mov_b32_e32 v25, v83
	v_mov_b32_e32 v168, v15
	v_mov_b32_e32 v169, v23
	v_mov_b32_e32 v99, v76
	v_lshl_add_u64 v[26:27], s[74:75], 0, v[24:25]
	v_lshl_add_u64 v[24:25], s[76:77], 0, v[24:25]
	v_pk_mul_f32 v[98:99], v[168:169], v[98:99]
	global_load_dwordx4 v[28:31], v[26:27], off nt
	s_nop 0
	global_load_dwordx4 v[24:27], v[24:25], off
	v_fma_f32 v57, v19, v174, v98
	v_and_b32_e32 v77, 0xffff0000, v77
	v_add_f32_e32 v57, v57, v99
	v_mov_b32_e32 v98, v19
	v_mov_b32_e32 v99, v23
	v_mul_f32_e32 v57, v57, v177
	v_pk_mul_f32 v[98:99], v[98:99], v[76:77]
	v_cvt_pk_bf16_f32 v57, v78, v57
	v_fma_f32 v78, v15, v174, v98
	v_add_f32_e32 v78, v78, v99
	v_mul_f32_e32 v98, v78, v183
	v_and_b32_e32 v78, 0xffff0000, v59
	v_mov_b32_e32 v170, v3
	v_mov_b32_e32 v171, v11
	v_mul_f32_e32 v81, v81, v180
	v_mul_f32_e32 v180, v97, v184
	v_mov_b32_e32 v97, v78
	v_pk_mul_f32 v[96:97], v[170:171], v[96:97]
	v_and_b32_e32 v79, 0xffff0000, v79
	v_fma_f32 v59, v7, v175, v96
	v_add_f32_e32 v59, v59, v97
	v_mul_f32_e32 v59, v59, v179
	v_cvt_pk_bf16_f32 v59, v155, v59
	global_store_dwordx4 v[100:101], v[56:59], off nt
	v_lshl_add_u64 v[94:95], v[132:133], 0, v[94:95]
	v_mov_b32_e32 v99, v112
	v_mov_b32_e32 v56, v7
	v_mov_b32_e32 v57, v11
	v_pk_mul_f32 v[56:57], v[56:57], v[78:79]
	v_cvt_pk_bf16_f32 v58, v180, v119
	v_fma_f32 v56, v3, v175, v56
	v_add_f32_e32 v56, v56, v57
	v_mul_f32_e32 v59, v56, v187
	v_cvt_pk_bf16_f32 v56, v81, v118
	v_cvt_pk_bf16_f32 v57, v154, v98
	v_cvt_pk_bf16_f32 v59, v102, v59
	global_store_dwordx4 v[94:95], v[56:59], off nt
	v_mov_b32_e32 v112, v107
	s_waitcnt vmcnt(13)
	v_lshlrev_b32_e32 v94, 16, v72
	v_mov_b32_e32 v59, v108
	v_mov_b32_e32 v108, v111
	v_mov_b32_e32 v58, v110
	v_pk_mul_f32 v[96:97], v[16:17], v[108:109]
	v_and_b32_e32 v95, 0xffff0000, v72
	v_pk_fma_f32 v[58:59], v[12:13], v[58:59], v[96:97]
	v_mov_b32_e32 v98, v106
	v_pk_mul_f32 v[100:101], v[4:5], v[112:113]
	s_waitcnt vmcnt(12)
	v_lshlrev_b32_e32 v56, 16, v68
	v_and_b32_e32 v57, 0xffff0000, v68
	v_pk_fma_f32 v[58:59], v[20:21], v[94:95], v[58:59]
	v_lshlrev_b32_e32 v96, 16, v74
	v_and_b32_e32 v97, 0xffff0000, v74
	v_pk_fma_f32 v[98:99], v[0:1], v[98:99], v[100:101]
	v_pk_mul_f32 v[56:57], v[58:59], v[56:57]
	v_lshlrev_b32_e32 v58, 16, v70
	v_and_b32_e32 v59, 0xffff0000, v70
	v_pk_fma_f32 v[98:99], v[8:9], v[96:97], v[98:99]
	v_lshlrev_b32_e32 v72, 16, v73
	v_pk_mul_f32 v[58:59], v[98:99], v[58:59]
	v_mov_b32_e32 v99, v76
	v_mov_b32_e32 v76, v115
	v_mov_b32_e32 v98, v114
	v_pk_mul_f32 v[100:101], v[18:19], v[76:77]
	v_and_b32_e32 v73, 0xffff0000, v73
	v_pk_fma_f32 v[98:99], v[14:15], v[98:99], v[100:101]
	v_lshlrev_b32_e32 v68, 16, v69
	v_and_b32_e32 v69, 0xffff0000, v69
	v_pk_fma_f32 v[98:99], v[22:23], v[72:73], v[98:99]
	v_lshlrev_b32_e32 v74, 16, v75
	v_pk_mul_f32 v[68:69], v[98:99], v[68:69]
	v_mov_b32_e32 v99, v78
	v_mov_b32_e32 v78, v117
	v_mov_b32_e32 v98, v116
	v_pk_mul_f32 v[100:101], v[6:7], v[78:79]
	v_and_b32_e32 v75, 0xffff0000, v75
	v_pk_fma_f32 v[98:99], v[2:3], v[98:99], v[100:101]
	v_lshlrev_b32_e32 v70, 16, v71
	v_and_b32_e32 v71, 0xffff0000, v71
	v_pk_fma_f32 v[98:99], v[10:11], v[74:75], v[98:99]
	v_cvt_pk_bf16_f32 v56, v56, v57
	v_pk_mul_f32 v[70:71], v[98:99], v[70:71]
	v_cvt_pk_bf16_f32 v57, v68, v69
	v_cvt_pk_bf16_f32 v58, v58, v59
	v_cvt_pk_bf16_f32 v59, v70, v71
	v_lshl_add_u64 v[68:69], v[132:133], 0, v[92:93]
	global_store_dwordx4 v[68:69], v[56:59], off nt
	s_waitcnt vmcnt(12)
	v_lshlrev_b32_e32 v68, 16, v64
	v_and_b32_e32 v69, 0xffff0000, v64
	v_pk_mul_f32 v[58:59], v[16:17], v[94:95]
	v_pk_mul_f32 v[92:93], v[4:5], v[96:97]
	v_pk_fma_f32 v[58:59], v[12:13], v[108:109], v[58:59]
	s_waitcnt vmcnt(11)
	v_lshlrev_b32_e32 v56, 16, v60
	v_and_b32_e32 v57, 0xffff0000, v60
	v_pk_fma_f32 v[58:59], v[20:21], v[68:69], v[58:59]
	v_lshlrev_b32_e32 v70, 16, v66
	v_and_b32_e32 v71, 0xffff0000, v66
	v_pk_fma_f32 v[92:93], v[0:1], v[112:113], v[92:93]
	v_pk_mul_f32 v[56:57], v[58:59], v[56:57]
	v_lshlrev_b32_e32 v58, 16, v62
	v_and_b32_e32 v59, 0xffff0000, v62
	v_pk_fma_f32 v[92:93], v[8:9], v[70:71], v[92:93]
	v_lshlrev_b32_e32 v64, 16, v65
	v_pk_mul_f32 v[58:59], v[92:93], v[58:59]
	v_pk_mul_f32 v[92:93], v[18:19], v[72:73]
	v_and_b32_e32 v65, 0xffff0000, v65
	v_pk_fma_f32 v[76:77], v[14:15], v[76:77], v[92:93]
	v_lshlrev_b32_e32 v60, 16, v61
	v_and_b32_e32 v61, 0xffff0000, v61
	v_pk_fma_f32 v[76:77], v[22:23], v[64:65], v[76:77]
	v_lshlrev_b32_e32 v66, 16, v67
	v_pk_mul_f32 v[60:61], v[76:77], v[60:61]
	v_pk_mul_f32 v[76:77], v[6:7], v[74:75]
	v_and_b32_e32 v67, 0xffff0000, v67
	v_pk_fma_f32 v[76:77], v[2:3], v[78:79], v[76:77]
	v_lshlrev_b32_e32 v62, 16, v63
	v_and_b32_e32 v63, 0xffff0000, v63
	v_pk_fma_f32 v[76:77], v[10:11], v[66:67], v[76:77]
	v_cvt_pk_bf16_f32 v56, v56, v57
	v_pk_mul_f32 v[62:63], v[76:77], v[62:63]
	v_cvt_pk_bf16_f32 v57, v60, v61
	v_cvt_pk_bf16_f32 v58, v58, v59
	v_cvt_pk_bf16_f32 v59, v62, v63
	v_lshl_add_u64 v[60:61], v[132:133], 0, v[90:91]
	global_store_dwordx4 v[60:61], v[56:59], off nt
	v_pk_mul_f32 v[60:61], v[16:17], v[68:69]
	v_pk_mul_f32 v[76:77], v[4:5], v[70:71]
	s_waitcnt vmcnt(11)
	v_lshlrev_b32_e32 v56, 16, v52
	v_and_b32_e32 v57, 0xffff0000, v52
	v_pk_fma_f32 v[60:61], v[12:13], v[94:95], v[60:61]
	s_waitcnt vmcnt(10)
	v_lshlrev_b32_e32 v58, 16, v48
	v_and_b32_e32 v59, 0xffff0000, v48
	v_pk_fma_f32 v[60:61], v[20:21], v[56:57], v[60:61]
	v_pk_fma_f32 v[76:77], v[0:1], v[96:97], v[76:77]
	v_pk_mul_f32 v[58:59], v[60:61], v[58:59]
	v_lshlrev_b32_e32 v60, 16, v54
	v_and_b32_e32 v61, 0xffff0000, v54
	v_lshlrev_b32_e32 v62, 16, v50
	v_and_b32_e32 v63, 0xffff0000, v50
	v_pk_fma_f32 v[76:77], v[8:9], v[60:61], v[76:77]
	v_lshlrev_b32_e32 v52, 16, v53
	v_pk_mul_f32 v[62:63], v[76:77], v[62:63]
	v_pk_mul_f32 v[76:77], v[18:19], v[64:65]
	v_and_b32_e32 v53, 0xffff0000, v53
	v_pk_fma_f32 v[72:73], v[14:15], v[72:73], v[76:77]
	v_lshlrev_b32_e32 v48, 16, v49
	v_and_b32_e32 v49, 0xffff0000, v49
	v_pk_fma_f32 v[72:73], v[22:23], v[52:53], v[72:73]
	v_lshlrev_b32_e32 v54, 16, v55
	v_pk_mul_f32 v[72:73], v[72:73], v[48:49]
	v_lshlrev_b32_e32 v48, 16, v51
	v_and_b32_e32 v49, 0xffff0000, v51
	v_pk_mul_f32 v[50:51], v[6:7], v[66:67]
	v_and_b32_e32 v55, 0xffff0000, v55
	v_pk_fma_f32 v[50:51], v[2:3], v[74:75], v[50:51]
	s_waitcnt vmcnt(7)
	v_lshlrev_b32_e32 v78, 16, v36
	v_pk_fma_f32 v[50:51], v[10:11], v[54:55], v[50:51]
	v_and_b32_e32 v79, 0xffff0000, v36
	v_pk_mul_f32 v[74:75], v[50:51], v[48:49]
	v_cvt_pk_bf16_f32 v48, v58, v59
	v_cvt_pk_bf16_f32 v49, v72, v73
	v_cvt_pk_bf16_f32 v50, v62, v63
	v_cvt_pk_bf16_f32 v51, v74, v75
	v_lshl_add_u64 v[58:59], v[132:133], 0, v[88:89]
	global_store_dwordx4 v[58:59], v[48:51], off nt
	v_pk_mul_f32 v[58:59], v[16:17], v[56:57]
	v_lshlrev_b32_e32 v62, 16, v42
	v_lshlrev_b32_e32 v48, 16, v44
	v_and_b32_e32 v49, 0xffff0000, v44
	v_pk_fma_f32 v[58:59], v[12:13], v[68:69], v[58:59]
	v_lshlrev_b32_e32 v50, 16, v40
	v_and_b32_e32 v51, 0xffff0000, v40
	v_pk_fma_f32 v[58:59], v[20:21], v[48:49], v[58:59]
	v_pk_mul_f32 v[68:69], v[4:5], v[60:61]
	v_pk_mul_f32 v[50:51], v[58:59], v[50:51]
	v_lshlrev_b32_e32 v58, 16, v46
	v_and_b32_e32 v59, 0xffff0000, v46
	v_pk_fma_f32 v[68:69], v[0:1], v[70:71], v[68:69]
	v_and_b32_e32 v63, 0xffff0000, v42
	v_pk_fma_f32 v[68:69], v[8:9], v[58:59], v[68:69]
	v_lshlrev_b32_e32 v44, 16, v45
	v_pk_mul_f32 v[62:63], v[68:69], v[62:63]
	v_pk_mul_f32 v[68:69], v[18:19], v[52:53]
	v_and_b32_e32 v45, 0xffff0000, v45
	v_pk_fma_f32 v[64:65], v[14:15], v[64:65], v[68:69]
	v_lshlrev_b32_e32 v40, 16, v41
	v_and_b32_e32 v41, 0xffff0000, v41
	v_pk_fma_f32 v[64:65], v[22:23], v[44:45], v[64:65]
	v_lshlrev_b32_e32 v46, 16, v47
	v_pk_mul_f32 v[64:65], v[64:65], v[40:41]
	v_lshlrev_b32_e32 v40, 16, v43
	v_and_b32_e32 v41, 0xffff0000, v43
	v_pk_mul_f32 v[42:43], v[6:7], v[54:55]
	v_and_b32_e32 v47, 0xffff0000, v47
	v_pk_fma_f32 v[42:43], v[2:3], v[66:67], v[42:43]
	v_lshlrev_b32_e32 v106, 16, v37
	v_pk_fma_f32 v[42:43], v[10:11], v[46:47], v[42:43]
	v_and_b32_e32 v107, 0xffff0000, v37
	v_pk_mul_f32 v[66:67], v[42:43], v[40:41]
	v_cvt_pk_bf16_f32 v40, v50, v51
	v_cvt_pk_bf16_f32 v41, v64, v65
	v_cvt_pk_bf16_f32 v42, v62, v63
	v_cvt_pk_bf16_f32 v43, v66, v67
	v_lshl_add_u64 v[50:51], v[132:133], 0, v[86:87]
	global_store_dwordx4 v[50:51], v[40:43], off nt
	v_pk_mul_f32 v[36:37], v[18:19], v[44:45]
	v_pk_mul_f32 v[50:51], v[4:5], v[58:59]
	v_pk_mul_f32 v[42:43], v[16:17], v[48:49]
	v_pk_fma_f32 v[36:37], v[14:15], v[52:53], v[36:37]
	v_pk_fma_f32 v[42:43], v[12:13], v[56:57], v[42:43]
	s_waitcnt vmcnt(8)
	v_lshlrev_b32_e32 v40, 16, v32
	v_and_b32_e32 v41, 0xffff0000, v32
	v_pk_fma_f32 v[42:43], v[20:21], v[78:79], v[42:43]
	v_lshlrev_b32_e32 v32, 16, v33
	v_and_b32_e32 v33, 0xffff0000, v33
	v_pk_fma_f32 v[36:37], v[22:23], v[106:107], v[36:37]
	v_pk_mul_f32 v[40:41], v[42:43], v[40:41]
	v_lshlrev_b32_e32 v42, 16, v34
	v_and_b32_e32 v43, 0xffff0000, v34
	v_pk_mul_f32 v[36:37], v[36:37], v[32:33]
	v_lshlrev_b32_e32 v32, 16, v35
	v_and_b32_e32 v33, 0xffff0000, v35
	v_pk_mul_f32 v[34:35], v[6:7], v[46:47]
	v_lshlrev_b32_e32 v102, 16, v38
	v_and_b32_e32 v103, 0xffff0000, v38
	v_pk_fma_f32 v[50:51], v[0:1], v[60:61], v[50:51]
	v_lshlrev_b32_e32 v108, 16, v39
	v_and_b32_e32 v109, 0xffff0000, v39
	v_pk_fma_f32 v[34:35], v[2:3], v[54:55], v[34:35]
	v_pk_fma_f32 v[50:51], v[8:9], v[102:103], v[50:51]
	v_pk_fma_f32 v[34:35], v[10:11], v[108:109], v[34:35]
	v_pk_mul_f32 v[42:43], v[50:51], v[42:43]
	v_pk_mul_f32 v[38:39], v[34:35], v[32:33]
	v_cvt_pk_bf16_f32 v32, v40, v41
	v_cvt_pk_bf16_f32 v33, v36, v37
	v_cvt_pk_bf16_f32 v34, v42, v43
	v_cvt_pk_bf16_f32 v35, v38, v39
	v_lshl_add_u64 v[36:37], v[132:133], 0, v[84:85]
	global_store_dwordx4 v[36:37], v[32:35], off nt
	s_waitcnt vmcnt(8)
	v_lshlrev_b32_e32 v110, 16, v28
	v_and_b32_e32 v111, 0xffff0000, v28
	v_pk_mul_f32 v[34:35], v[16:17], v[78:79]
	v_lshlrev_b32_e32 v114, 16, v29
	v_and_b32_e32 v115, 0xffff0000, v29
	v_pk_mul_f32 v[28:29], v[18:19], v[106:107]
	v_pk_fma_f32 v[34:35], v[12:13], v[48:49], v[34:35]
	v_pk_fma_f32 v[28:29], v[14:15], v[44:45], v[28:29]
	s_waitcnt vmcnt(7)
	v_lshlrev_b32_e32 v32, 16, v24
	v_and_b32_e32 v33, 0xffff0000, v24
	v_pk_fma_f32 v[34:35], v[20:21], v[110:111], v[34:35]
	v_lshlrev_b32_e32 v24, 16, v25
	v_and_b32_e32 v25, 0xffff0000, v25
	v_pk_fma_f32 v[28:29], v[22:23], v[114:115], v[28:29]
	v_pk_mul_f32 v[32:33], v[34:35], v[32:33]
	v_lshlrev_b32_e32 v34, 16, v26
	v_and_b32_e32 v35, 0xffff0000, v26
	v_pk_mul_f32 v[36:37], v[4:5], v[102:103]
	v_pk_mul_f32 v[28:29], v[28:29], v[24:25]
	v_lshlrev_b32_e32 v24, 16, v27
	v_and_b32_e32 v25, 0xffff0000, v27
	v_pk_mul_f32 v[26:27], v[6:7], v[108:109]
	v_lshlrev_b32_e32 v112, 16, v30
	v_and_b32_e32 v113, 0xffff0000, v30
	v_pk_fma_f32 v[36:37], v[0:1], v[58:59], v[36:37]
	v_lshlrev_b32_e32 v116, 16, v31
	v_and_b32_e32 v117, 0xffff0000, v31
	v_pk_fma_f32 v[26:27], v[2:3], v[46:47], v[26:27]
	v_pk_fma_f32 v[36:37], v[8:9], v[112:113], v[36:37]
	v_pk_fma_f32 v[26:27], v[10:11], v[116:117], v[26:27]
	v_pk_mul_f32 v[34:35], v[36:37], v[34:35]
	v_pk_mul_f32 v[30:31], v[26:27], v[24:25]
	v_cvt_pk_bf16_f32 v24, v32, v33
	v_cvt_pk_bf16_f32 v25, v28, v29
	v_cvt_pk_bf16_f32 v26, v34, v35
	v_cvt_pk_bf16_f32 v27, v30, v31
	v_lshl_add_u64 v[28:29], v[132:133], 0, v[82:83]
	global_store_dwordx4 v[28:29], v[24:27], off nt
	v_pk_mul_f32 v[164:165], v[16:17], v[110:111]
	v_pk_mul_f32 v[166:167], v[4:5], v[112:113]
	v_add_u32_e32 v24, 8, v80
	v_ashrrev_i32_e32 v25, 31, v24
	v_lshlrev_b64 v[118:119], 11, v[24:25]
	v_or_b32_e32 v24, v118, v105
	v_mov_b32_e32 v25, v119
	v_lshl_add_u64 v[26:27], s[74:75], 0, v[24:25]
	global_load_dwordx4 v[74:77], v[26:27], off nt
	v_lshl_add_u64 v[24:25], s[76:77], 0, v[24:25]
	global_load_dwordx4 v[82:85], v[24:25], off
	v_add_u32_e32 v24, 9, v80
	v_ashrrev_i32_e32 v25, 31, v24
	v_lshlrev_b64 v[154:155], 11, v[24:25]
	v_or_b32_e32 v24, v154, v105
	v_mov_b32_e32 v25, v155
	v_lshl_add_u64 v[26:27], s[74:75], 0, v[24:25]
	v_lshl_add_u64 v[24:25], s[76:77], 0, v[24:25]
	global_load_dwordx4 v[86:89], v[26:27], off nt
	global_load_dwordx4 v[90:93], v[24:25], off
	v_add_u32_e32 v24, 10, v80
	v_ashrrev_i32_e32 v25, 31, v24
	v_lshlrev_b64 v[156:157], 11, v[24:25]
	v_or_b32_e32 v24, v156, v105
	v_mov_b32_e32 v25, v157
	v_lshl_add_u64 v[26:27], s[74:75], 0, v[24:25]
	v_lshl_add_u64 v[24:25], s[76:77], 0, v[24:25]
	global_load_dwordx4 v[94:97], v[26:27], off nt
	global_load_dwordx4 v[98:101], v[24:25], off
	v_add_u32_e32 v24, 11, v80
	v_ashrrev_i32_e32 v25, 31, v24
	v_lshlrev_b64 v[72:73], 11, v[24:25]
	v_or_b32_e32 v24, v72, v105
	v_mov_b32_e32 v25, v73
	v_lshl_add_u64 v[26:27], s[74:75], 0, v[24:25]
	v_lshl_add_u64 v[24:25], s[76:77], 0, v[24:25]
	global_load_dwordx4 v[60:63], v[26:27], off nt
	global_load_dwordx4 v[56:59], v[24:25], off
	v_add_u32_e32 v24, 12, v80
	v_ashrrev_i32_e32 v25, 31, v24
	v_lshlrev_b64 v[70:71], 11, v[24:25]
	v_or_b32_e32 v24, v70, v105
	v_mov_b32_e32 v25, v71
	v_lshl_add_u64 v[26:27], s[74:75], 0, v[24:25]
	v_lshl_add_u64 v[24:25], s[76:77], 0, v[24:25]
	global_load_dwordx4 v[52:55], v[26:27], off nt
	global_load_dwordx4 v[48:51], v[24:25], off
	v_add_u32_e32 v24, 13, v80
	v_ashrrev_i32_e32 v25, 31, v24
	v_lshlrev_b64 v[68:69], 11, v[24:25]
	v_or_b32_e32 v24, v68, v105
	v_mov_b32_e32 v25, v69
	v_lshl_add_u64 v[26:27], s[74:75], 0, v[24:25]
	v_lshl_add_u64 v[24:25], s[76:77], 0, v[24:25]
	global_load_dwordx4 v[44:47], v[26:27], off nt
	global_load_dwordx4 v[40:43], v[24:25], off
	v_add_u32_e32 v24, 14, v80
	v_ashrrev_i32_e32 v25, 31, v24
	v_lshlrev_b64 v[66:67], 11, v[24:25]
	v_or_b32_e32 v24, v66, v105
	v_mov_b32_e32 v25, v67
	v_lshl_add_u64 v[26:27], s[74:75], 0, v[24:25]
	v_lshl_add_u64 v[24:25], s[76:77], 0, v[24:25]
	global_load_dwordx4 v[36:39], v[26:27], off nt
	global_load_dwordx4 v[32:35], v[24:25], off
	v_pk_fma_f32 v[78:79], v[12:13], v[78:79], v[164:165]
	v_add_u32_e32 v24, 15, v80
	v_pk_fma_f32 v[102:103], v[0:1], v[102:103], v[166:167]
	v_ashrrev_i32_e32 v25, 31, v24
	v_lshlrev_b64 v[64:65], 11, v[24:25]
	v_or_b32_e32 v24, v64, v105
	v_mov_b32_e32 v25, v65
	v_lshl_add_u64 v[26:27], s[74:75], 0, v[24:25]
	v_lshl_add_u64 v[24:25], s[76:77], 0, v[24:25]
	global_load_dwordx4 v[28:31], v[26:27], off nt
	s_nop 0
	global_load_dwordx4 v[24:27], v[24:25], off
	v_lshl_add_u64 v[72:73], v[132:133], 0, v[72:73]
	s_waitcnt vmcnt(15)
	v_lshlrev_b32_e32 v160, 16, v74
	v_and_b32_e32 v161, 0xffff0000, v74
	s_waitcnt vmcnt(14)
	v_lshlrev_b32_e32 v162, 16, v82
	v_and_b32_e32 v163, 0xffff0000, v82
	v_pk_fma_f32 v[78:79], v[20:21], v[160:161], v[78:79]
	v_lshlrev_b32_e32 v164, 16, v84
	v_pk_mul_f32 v[78:79], v[78:79], v[162:163]
	v_lshlrev_b32_e32 v162, 16, v76
	v_and_b32_e32 v163, 0xffff0000, v76
	v_and_b32_e32 v165, 0xffff0000, v84
	v_pk_fma_f32 v[102:103], v[8:9], v[162:163], v[102:103]
	v_lshlrev_b32_e32 v74, 16, v83
	v_pk_mul_f32 v[102:103], v[102:103], v[164:165]
	v_lshlrev_b32_e32 v164, 16, v75
	v_and_b32_e32 v165, 0xffff0000, v75
	v_and_b32_e32 v75, 0xffff0000, v83
	v_pk_mul_f32 v[82:83], v[18:19], v[114:115]
	s_nop 0
	v_pk_fma_f32 v[82:83], v[14:15], v[106:107], v[82:83]
	v_lshlrev_b32_e32 v106, 16, v77
	v_and_b32_e32 v107, 0xffff0000, v77
	v_pk_mul_f32 v[76:77], v[6:7], v[116:117]
	v_pk_fma_f32 v[82:83], v[22:23], v[164:165], v[82:83]
	v_pk_fma_f32 v[76:77], v[2:3], v[108:109], v[76:77]
	v_pk_mul_f32 v[82:83], v[82:83], v[74:75]
	v_lshlrev_b32_e32 v74, 16, v85
	v_and_b32_e32 v75, 0xffff0000, v85
	v_pk_fma_f32 v[76:77], v[10:11], v[106:107], v[76:77]
	s_nop 0
	v_pk_mul_f32 v[84:85], v[76:77], v[74:75]
	v_cvt_pk_bf16_f32 v74, v78, v79
	v_cvt_pk_bf16_f32 v75, v82, v83
	v_cvt_pk_bf16_f32 v76, v102, v103
	v_cvt_pk_bf16_f32 v77, v84, v85
	v_lshl_add_u64 v[78:79], v[132:133], 0, v[118:119]
	global_store_dwordx4 v[78:79], v[74:77], off nt
	s_waitcnt vmcnt(14)
	v_lshlrev_b32_e32 v78, 16, v86
	v_and_b32_e32 v79, 0xffff0000, v86
	v_pk_mul_f32 v[76:77], v[16:17], v[160:161]
	v_pk_mul_f32 v[84:85], v[4:5], v[162:163]
	v_pk_fma_f32 v[76:77], v[12:13], v[110:111], v[76:77]
	s_waitcnt vmcnt(13)
	v_lshlrev_b32_e32 v74, 16, v90
	v_and_b32_e32 v75, 0xffff0000, v90
	v_pk_fma_f32 v[76:77], v[20:21], v[78:79], v[76:77]
	v_lshlrev_b32_e32 v82, 16, v88
	v_and_b32_e32 v83, 0xffff0000, v88
	v_pk_fma_f32 v[84:85], v[0:1], v[112:113], v[84:85]
	v_pk_mul_f32 v[74:75], v[76:77], v[74:75]
	v_lshlrev_b32_e32 v76, 16, v92
	v_and_b32_e32 v77, 0xffff0000, v92
	v_pk_fma_f32 v[84:85], v[8:9], v[82:83], v[84:85]
	v_lshlrev_b32_e32 v86, 16, v91
	v_pk_mul_f32 v[76:77], v[84:85], v[76:77]
	v_lshlrev_b32_e32 v84, 16, v87
	v_and_b32_e32 v85, 0xffff0000, v87
	v_and_b32_e32 v87, 0xffff0000, v91
	v_pk_mul_f32 v[90:91], v[18:19], v[164:165]
	v_lshlrev_b32_e32 v88, 16, v89
	v_pk_fma_f32 v[90:91], v[14:15], v[114:115], v[90:91]
	v_and_b32_e32 v89, 0xffff0000, v89
	v_pk_fma_f32 v[90:91], v[22:23], v[84:85], v[90:91]
	v_cvt_pk_bf16_f32 v74, v74, v75
	v_pk_mul_f32 v[86:87], v[90:91], v[86:87]
	v_lshlrev_b32_e32 v90, 16, v93
	v_and_b32_e32 v91, 0xffff0000, v93
	v_pk_mul_f32 v[92:93], v[6:7], v[106:107]
	v_cvt_pk_bf16_f32 v75, v86, v87
	v_pk_fma_f32 v[92:93], v[2:3], v[116:117], v[92:93]
	v_cvt_pk_bf16_f32 v76, v76, v77
	v_pk_fma_f32 v[92:93], v[10:11], v[88:89], v[92:93]
	v_lshl_add_u64 v[86:87], v[132:133], 0, v[154:155]
	v_pk_mul_f32 v[90:91], v[92:93], v[90:91]
	v_pk_mul_f32 v[92:93], v[4:5], v[82:83]
	v_cvt_pk_bf16_f32 v77, v90, v91
	global_store_dwordx4 v[86:87], v[74:77], off nt
	s_waitcnt vmcnt(13)
	v_lshlrev_b32_e32 v86, 16, v94
	v_and_b32_e32 v87, 0xffff0000, v94
	v_pk_mul_f32 v[76:77], v[16:17], v[78:79]
	s_waitcnt vmcnt(12)
	v_lshlrev_b32_e32 v74, 16, v98
	v_pk_fma_f32 v[76:77], v[12:13], v[160:161], v[76:77]
	v_and_b32_e32 v75, 0xffff0000, v98
	v_pk_fma_f32 v[76:77], v[20:21], v[86:87], v[76:77]
	v_lshlrev_b32_e32 v90, 16, v96
	v_and_b32_e32 v91, 0xffff0000, v96
	v_pk_fma_f32 v[92:93], v[0:1], v[162:163], v[92:93]
	v_pk_mul_f32 v[74:75], v[76:77], v[74:75]
	v_lshlrev_b32_e32 v76, 16, v100
	v_and_b32_e32 v77, 0xffff0000, v100
	v_pk_fma_f32 v[92:93], v[8:9], v[90:91], v[92:93]
	v_lshlrev_b32_e32 v94, 16, v99
	v_pk_mul_f32 v[76:77], v[92:93], v[76:77]
	v_lshlrev_b32_e32 v92, 16, v95
	v_and_b32_e32 v93, 0xffff0000, v95
	v_and_b32_e32 v95, 0xffff0000, v99
	v_pk_mul_f32 v[98:99], v[18:19], v[84:85]
	v_lshlrev_b32_e32 v96, 16, v97
	v_pk_fma_f32 v[98:99], v[14:15], v[164:165], v[98:99]
	v_and_b32_e32 v97, 0xffff0000, v97
	v_pk_fma_f32 v[98:99], v[22:23], v[92:93], v[98:99]
	v_cvt_pk_bf16_f32 v74, v74, v75
	v_pk_mul_f32 v[94:95], v[98:99], v[94:95]
	v_lshlrev_b32_e32 v98, 16, v101
	v_and_b32_e32 v99, 0xffff0000, v101
	v_pk_mul_f32 v[100:101], v[6:7], v[88:89]
	v_cvt_pk_bf16_f32 v75, v94, v95
	v_pk_fma_f32 v[100:101], v[2:3], v[106:107], v[100:101]
	v_cvt_pk_bf16_f32 v76, v76, v77
	v_pk_fma_f32 v[100:101], v[10:11], v[96:97], v[100:101]
	v_lshl_add_u64 v[94:95], v[132:133], 0, v[156:157]
	v_pk_mul_f32 v[98:99], v[100:101], v[98:99]
	s_nop 0
	v_cvt_pk_bf16_f32 v77, v98, v99
	global_store_dwordx4 v[94:95], v[74:77], off nt
	v_pk_mul_f32 v[94:95], v[16:17], v[86:87]
	v_pk_mul_f32 v[98:99], v[4:5], v[90:91]
	s_waitcnt vmcnt(12)
	v_lshlrev_b32_e32 v74, 16, v60
	v_and_b32_e32 v75, 0xffff0000, v60
	v_pk_fma_f32 v[78:79], v[12:13], v[78:79], v[94:95]
	s_waitcnt vmcnt(11)
	v_lshlrev_b32_e32 v76, 16, v56
	v_and_b32_e32 v77, 0xffff0000, v56
	v_pk_fma_f32 v[78:79], v[20:21], v[74:75], v[78:79]
	v_pk_fma_f32 v[82:83], v[0:1], v[82:83], v[98:99]
	v_pk_mul_f32 v[76:77], v[78:79], v[76:77]
	v_lshlrev_b32_e32 v78, 16, v62
	v_and_b32_e32 v79, 0xffff0000, v62
	v_lshlrev_b32_e32 v94, 16, v58
	v_and_b32_e32 v95, 0xffff0000, v58
	v_pk_fma_f32 v[82:83], v[8:9], v[78:79], v[82:83]
	v_lshlrev_b32_e32 v60, 16, v61
	v_pk_mul_f32 v[82:83], v[82:83], v[94:95]
	v_pk_mul_f32 v[94:95], v[18:19], v[92:93]
	v_and_b32_e32 v61, 0xffff0000, v61
	v_pk_fma_f32 v[84:85], v[14:15], v[84:85], v[94:95]
	v_lshlrev_b32_e32 v56, 16, v57
	v_and_b32_e32 v57, 0xffff0000, v57
	v_pk_fma_f32 v[84:85], v[22:23], v[60:61], v[84:85]
	v_lshlrev_b32_e32 v62, 16, v63
	v_pk_mul_f32 v[84:85], v[84:85], v[56:57]
	v_lshlrev_b32_e32 v56, 16, v59
	v_and_b32_e32 v57, 0xffff0000, v59
	v_pk_mul_f32 v[58:59], v[6:7], v[96:97]
	v_and_b32_e32 v63, 0xffff0000, v63
	v_pk_fma_f32 v[58:59], v[2:3], v[88:89], v[58:59]
	s_nop 0
	v_pk_fma_f32 v[58:59], v[10:11], v[62:63], v[58:59]
	s_nop 0
	v_pk_mul_f32 v[88:89], v[58:59], v[56:57]
	v_cvt_pk_bf16_f32 v56, v76, v77
	v_cvt_pk_bf16_f32 v57, v84, v85
	v_cvt_pk_bf16_f32 v58, v82, v83
	v_cvt_pk_bf16_f32 v59, v88, v89
	global_store_dwordx4 v[72:73], v[56:59], off nt
	v_pk_mul_f32 v[72:73], v[16:17], v[74:75]
	v_pk_mul_f32 v[82:83], v[4:5], v[78:79]
	s_waitcnt vmcnt(11)
	v_lshlrev_b32_e32 v56, 16, v52
	v_and_b32_e32 v57, 0xffff0000, v52
	v_pk_fma_f32 v[72:73], v[12:13], v[86:87], v[72:73]
	s_waitcnt vmcnt(10)
	v_lshlrev_b32_e32 v58, 16, v48
	v_and_b32_e32 v59, 0xffff0000, v48
	v_pk_fma_f32 v[72:73], v[20:21], v[56:57], v[72:73]
	v_pk_fma_f32 v[82:83], v[0:1], v[90:91], v[82:83]
	v_pk_mul_f32 v[58:59], v[72:73], v[58:59]
	v_lshlrev_b32_e32 v72, 16, v54
	v_and_b32_e32 v73, 0xffff0000, v54
	v_lshlrev_b32_e32 v76, 16, v50
	v_and_b32_e32 v77, 0xffff0000, v50
	v_pk_fma_f32 v[82:83], v[8:9], v[72:73], v[82:83]
	v_lshlrev_b32_e32 v52, 16, v53
	v_pk_mul_f32 v[76:77], v[82:83], v[76:77]
	v_pk_mul_f32 v[82:83], v[18:19], v[60:61]
	v_and_b32_e32 v53, 0xffff0000, v53
	v_pk_fma_f32 v[82:83], v[14:15], v[92:93], v[82:83]
	v_lshlrev_b32_e32 v48, 16, v49
	v_and_b32_e32 v49, 0xffff0000, v49
	v_pk_fma_f32 v[82:83], v[22:23], v[52:53], v[82:83]
	v_lshlrev_b32_e32 v54, 16, v55
	v_pk_mul_f32 v[82:83], v[82:83], v[48:49]
	v_lshlrev_b32_e32 v48, 16, v51
	v_and_b32_e32 v49, 0xffff0000, v51
	v_pk_mul_f32 v[50:51], v[6:7], v[62:63]
	v_and_b32_e32 v55, 0xffff0000, v55
	v_pk_fma_f32 v[50:51], v[2:3], v[96:97], v[50:51]
	s_nop 0
	v_pk_fma_f32 v[50:51], v[10:11], v[54:55], v[50:51]
	s_nop 0
	v_pk_mul_f32 v[84:85], v[50:51], v[48:49]
	v_cvt_pk_bf16_f32 v48, v58, v59
	v_cvt_pk_bf16_f32 v49, v82, v83
	v_cvt_pk_bf16_f32 v50, v76, v77
	v_cvt_pk_bf16_f32 v51, v84, v85
	v_lshl_add_u64 v[58:59], v[132:133], 0, v[70:71]
	global_store_dwordx4 v[58:59], v[48:51], off nt
	v_pk_mul_f32 v[58:59], v[16:17], v[56:57]
	s_waitcnt vmcnt(9)
	v_lshlrev_b32_e32 v70, 16, v42
	v_lshlrev_b32_e32 v48, 16, v44
	v_and_b32_e32 v49, 0xffff0000, v44
	v_pk_fma_f32 v[58:59], v[12:13], v[74:75], v[58:59]
	v_lshlrev_b32_e32 v50, 16, v40
	v_and_b32_e32 v51, 0xffff0000, v40
	v_pk_fma_f32 v[58:59], v[20:21], v[48:49], v[58:59]
	v_pk_mul_f32 v[74:75], v[4:5], v[72:73]
	v_pk_mul_f32 v[50:51], v[58:59], v[50:51]
	v_lshlrev_b32_e32 v58, 16, v46
	v_and_b32_e32 v59, 0xffff0000, v46
	v_pk_fma_f32 v[74:75], v[0:1], v[78:79], v[74:75]
	v_and_b32_e32 v71, 0xffff0000, v42
	v_pk_fma_f32 v[74:75], v[8:9], v[58:59], v[74:75]
	v_lshlrev_b32_e32 v40, 16, v41
	v_pk_mul_f32 v[70:71], v[74:75], v[70:71]
	v_lshlrev_b32_e32 v74, 16, v45
	v_and_b32_e32 v75, 0xffff0000, v45
	v_pk_mul_f32 v[44:45], v[18:19], v[52:53]
	v_and_b32_e32 v41, 0xffff0000, v41
	v_pk_fma_f32 v[44:45], v[14:15], v[60:61], v[44:45]
	v_lshlrev_b32_e32 v60, 16, v47
	v_pk_fma_f32 v[44:45], v[22:23], v[74:75], v[44:45]
	v_and_b32_e32 v61, 0xffff0000, v47
	v_pk_mul_f32 v[44:45], v[44:45], v[40:41]
	v_lshlrev_b32_e32 v40, 16, v43
	v_and_b32_e32 v41, 0xffff0000, v43
	v_pk_mul_f32 v[42:43], v[6:7], v[54:55]
	s_nop 0
	v_pk_fma_f32 v[42:43], v[2:3], v[62:63], v[42:43]
	s_nop 0
	v_pk_fma_f32 v[42:43], v[10:11], v[60:61], v[42:43]
	s_nop 0
	v_pk_mul_f32 v[46:47], v[42:43], v[40:41]
	v_cvt_pk_bf16_f32 v40, v50, v51
	v_cvt_pk_bf16_f32 v41, v44, v45
	v_cvt_pk_bf16_f32 v42, v70, v71
	v_cvt_pk_bf16_f32 v43, v46, v47
	v_lshl_add_u64 v[44:45], v[132:133], 0, v[68:69]
	global_store_dwordx4 v[44:45], v[40:43], off nt
	v_pk_mul_f32 v[44:45], v[16:17], v[48:49]
	v_pk_mul_f32 v[46:47], v[4:5], v[58:59]
	s_waitcnt vmcnt(9)
	v_lshlrev_b32_e32 v40, 16, v36
	v_and_b32_e32 v41, 0xffff0000, v36
	v_pk_fma_f32 v[44:45], v[12:13], v[56:57], v[44:45]
	s_waitcnt vmcnt(8)
	v_lshlrev_b32_e32 v42, 16, v32
	v_and_b32_e32 v43, 0xffff0000, v32
	v_pk_fma_f32 v[44:45], v[20:21], v[40:41], v[44:45]
	v_pk_fma_f32 v[46:47], v[0:1], v[72:73], v[46:47]
	v_pk_mul_f32 v[50:51], v[44:45], v[42:43]
	v_lshlrev_b32_e32 v44, 16, v38
	v_and_b32_e32 v45, 0xffff0000, v38
	v_lshlrev_b32_e32 v42, 16, v34
	v_and_b32_e32 v43, 0xffff0000, v34
	v_pk_fma_f32 v[46:47], v[8:9], v[44:45], v[46:47]
	v_lshlrev_b32_e32 v32, 16, v33
	v_pk_mul_f32 v[56:57], v[46:47], v[42:43]
	v_lshlrev_b32_e32 v42, 16, v37
	v_and_b32_e32 v43, 0xffff0000, v37
	v_pk_mul_f32 v[36:37], v[18:19], v[74:75]
	v_and_b32_e32 v33, 0xffff0000, v33
	v_pk_fma_f32 v[36:37], v[14:15], v[52:53], v[36:37]
	v_lshlrev_b32_e32 v46, 16, v39
	v_pk_fma_f32 v[36:37], v[22:23], v[42:43], v[36:37]
	v_and_b32_e32 v47, 0xffff0000, v39
	v_pk_mul_f32 v[36:37], v[36:37], v[32:33]
	v_lshlrev_b32_e32 v32, 16, v35
	v_and_b32_e32 v33, 0xffff0000, v35
	v_pk_mul_f32 v[34:35], v[6:7], v[60:61]
	v_pk_mul_f32 v[16:17], v[16:17], v[40:41]
	v_pk_fma_f32 v[34:35], v[2:3], v[54:55], v[34:35]
	v_pk_fma_f32 v[12:13], v[12:13], v[48:49], v[16:17]
	v_pk_fma_f32 v[34:35], v[10:11], v[46:47], v[34:35]
	v_pk_mul_f32 v[4:5], v[4:5], v[44:45]
	v_pk_mul_f32 v[38:39], v[34:35], v[32:33]
	v_cvt_pk_bf16_f32 v32, v50, v51
	v_cvt_pk_bf16_f32 v33, v36, v37
	v_cvt_pk_bf16_f32 v34, v56, v57
	v_cvt_pk_bf16_f32 v35, v38, v39
	v_lshl_add_u64 v[36:37], v[132:133], 0, v[66:67]
	global_store_dwordx4 v[36:37], v[32:35], off nt
	v_pk_fma_f32 v[0:1], v[0:1], v[58:59], v[4:5]
	v_pk_mul_f32 v[6:7], v[6:7], v[46:47]
	s_waitcnt vmcnt(8)
	v_lshlrev_b32_e32 v32, 16, v28
	v_and_b32_e32 v33, 0xffff0000, v28
	s_waitcnt vmcnt(7)
	v_lshlrev_b32_e32 v34, 16, v24
	v_and_b32_e32 v35, 0xffff0000, v24
	v_pk_fma_f32 v[12:13], v[20:21], v[32:33], v[12:13]
	v_lshlrev_b32_e32 v20, 16, v26
	v_pk_mul_f32 v[16:17], v[12:13], v[34:35]
	v_lshlrev_b32_e32 v12, 16, v30
	v_and_b32_e32 v13, 0xffff0000, v30
	v_pk_fma_f32 v[0:1], v[8:9], v[12:13], v[0:1]
	v_pk_mul_f32 v[8:9], v[18:19], v[42:43]
	v_and_b32_e32 v21, 0xffff0000, v26
	v_lshlrev_b32_e32 v34, 16, v29
	v_and_b32_e32 v35, 0xffff0000, v29
	v_pk_fma_f32 v[8:9], v[14:15], v[74:75], v[8:9]
	v_pk_mul_f32 v[4:5], v[0:1], v[20:21]
	v_lshlrev_b32_e32 v0, 16, v25
	v_and_b32_e32 v1, 0xffff0000, v25
	v_pk_fma_f32 v[8:9], v[22:23], v[34:35], v[8:9]
	v_lshlrev_b32_e32 v14, 16, v31
	v_and_b32_e32 v15, 0xffff0000, v31
	v_pk_fma_f32 v[2:3], v[2:3], v[60:61], v[6:7]
	v_pk_mul_f32 v[8:9], v[8:9], v[0:1]
	v_lshlrev_b32_e32 v0, 16, v27
	v_and_b32_e32 v1, 0xffff0000, v27
	v_pk_fma_f32 v[2:3], v[10:11], v[14:15], v[2:3]
	s_nop 0
	v_pk_mul_f32 v[6:7], v[2:3], v[0:1]
	v_cvt_pk_bf16_f32 v0, v16, v17
	v_cvt_pk_bf16_f32 v1, v8, v9
	v_cvt_pk_bf16_f32 v2, v4, v5
	v_cvt_pk_bf16_f32 v3, v6, v7
	v_lshl_add_u64 v[4:5], v[132:133], 0, v[64:65]
	global_store_dwordx4 v[4:5], v[0:3], off nt
	s_nop 1
	v_or_b32_e32 v0, 15, v104
	v_cndmask_b32_e32 v1, 31, v243, vcc
	v_cmp_eq_u32_e64 s[0:1], v0, v1
	s_and_saveexec_b64 s[10:11], s[0:1]
	s_cbranch_execz .LBB0_410
	v_ashrrev_i32_e32 v0, 11, v80
	v_mov_b32_e32 v1, s31
	v_mov_b32_e32 v2, s49
	v_cndmask_b32_e32 v0, v194, v0, vcc
	v_cndmask_b32_e32 v3, v1, v2, vcc
	v_mov_b32_e32 v1, s30
	v_mov_b32_e32 v2, s48
	v_cndmask_b32_e32 v2, v1, v2, vcc
	v_ashrrev_i32_e32 v1, 31, v0
	v_lshlrev_b64 v[0:1], 13, v[0:1]
	v_lshl_add_u64 v[0:1], v[2:3], 0, v[0:1]
	v_lshlrev_b32_e32 v194, 2, v120
	v_lshl_add_u64 v[0:1], v[0:1], 0, v[194:195]
	global_store_dwordx4 v[0:1], v[40:43], off nt
	global_store_dwordx4 v[0:1], v[44:47], off offset:16
	v_add_co_u32_e32 v0, vcc, 0x1000, v0
	s_nop 1
	v_addc_co_u32_e32 v1, vcc, 0, v1, vcc
	global_store_dwordx4 v[0:1], v[32:35], off nt
	global_store_dwordx4 v[0:1], v[12:15], off offset:16
	s_branch .LBB0_410
